# v25b: v15 + int8 GEMM K-loop without VALU in its load phases (LDS-DMA loads in scalar-base form, LDS read addresses precomputed per tile)
# speedup vs baseline: 1.0012x; 1.0012x over previous
.LBB0_308:
	s_ashr_i32 s19, s18, 31
	s_lshl_b64 s[26:27], s[18:19], 18
	s_add_u32 s42, s38, s26
	s_addc_u32 s43, s39, s27
	s_and_b64 s[26:27], s[40:41], exec
	s_cselect_b32 s19, s43, s49
	s_cselect_b32 s63, s42, s48
	s_ashr_i32 s17, s16, 31
	s_lshl_b64 s[26:27], s[16:17], 19
	s_add_u32 s44, s54, s26
	s_addc_u32 s45, s55, s27
	s_and_b64 s[26:27], s[40:41], exec
	s_cselect_b32 s17, s45, s51
	s_cselect_b32 s64, s44, s50
	s_add_u32 s48, s48, 0x40080
	s_addc_u32 s49, s49, 0
	s_add_u32 s65, s50, 0x100
	v_mov_b32_e32 v0, 0
	s_addc_u32 s66, s51, 0
	s_mov_b32 s67, -2
	v_mov_b32_e32 v1, v0
	v_mov_b32_e32 v2, v0
	v_mov_b32_e32 v3, v0
	v_mov_b32_e32 v4, v0
	v_mov_b32_e32 v5, v0
	v_mov_b32_e32 v6, v0
	v_mov_b32_e32 v7, v0
	v_mov_b32_e32 v16, v0
	v_mov_b32_e32 v17, v0
	v_mov_b32_e32 v18, v0
	v_mov_b32_e32 v19, v0
	v_mov_b32_e32 v20, v0
	v_mov_b32_e32 v21, v0
	v_mov_b32_e32 v22, v0
	v_mov_b32_e32 v23, v0
	v_mov_b32_e32 v32, v0
	v_mov_b32_e32 v33, v0
	v_mov_b32_e32 v34, v0
	v_mov_b32_e32 v35, v0
	v_mov_b32_e32 v36, v0
	v_mov_b32_e32 v37, v0
	v_mov_b32_e32 v38, v0
	v_mov_b32_e32 v39, v0
	v_mov_b32_e32 v48, v0
	v_mov_b32_e32 v49, v0
	v_mov_b32_e32 v50, v0
	v_mov_b32_e32 v51, v0
	v_mov_b32_e32 v52, v0
	v_mov_b32_e32 v53, v0
	v_mov_b32_e32 v54, v0
	v_mov_b32_e32 v55, v0
	v_mov_b32_e32 v8, v0
	v_mov_b32_e32 v9, v0
	v_mov_b32_e32 v10, v0
	v_mov_b32_e32 v11, v0
	v_mov_b32_e32 v12, v0
	v_mov_b32_e32 v13, v0
	v_mov_b32_e32 v14, v0
	v_mov_b32_e32 v15, v0
	v_mov_b32_e32 v24, v0
	v_mov_b32_e32 v25, v0
	v_mov_b32_e32 v26, v0
	v_mov_b32_e32 v27, v0
	v_mov_b32_e32 v28, v0
	v_mov_b32_e32 v29, v0
	v_mov_b32_e32 v30, v0
	v_mov_b32_e32 v31, v0
	v_mov_b32_e32 v40, v0
	v_mov_b32_e32 v41, v0
	v_mov_b32_e32 v42, v0
	v_mov_b32_e32 v43, v0
	v_mov_b32_e32 v44, v0
	v_mov_b32_e32 v45, v0
	v_mov_b32_e32 v46, v0
	v_mov_b32_e32 v47, v0
	v_mov_b32_e32 v64, v0
	v_mov_b32_e32 v65, v0
	v_mov_b32_e32 v66, v0
	v_mov_b32_e32 v67, v0
	v_mov_b32_e32 v76, v0
	v_mov_b32_e32 v77, v0
	v_mov_b32_e32 v78, v0
	v_mov_b32_e32 v79, v0
	v_mov_b32_e32 v80, v0
	v_mov_b32_e32 v81, v0
	v_mov_b32_e32 v82, v0
	v_mov_b32_e32 v83, v0
	v_mov_b32_e32 v84, v0
	v_mov_b32_e32 v85, v0
	v_mov_b32_e32 v86, v0
	v_mov_b32_e32 v87, v0
	v_mov_b32_e32 v98, v0
	v_mov_b32_e32 v99, v0
	v_mov_b32_e32 v100, v0
	v_mov_b32_e32 v101, v0
	v_mov_b32_e32 v102, v0
	v_mov_b32_e32 v103, v0
	v_mov_b32_e32 v104, v0
	v_mov_b32_e32 v105, v0
	v_mov_b32_e32 v114, v0
	v_mov_b32_e32 v115, v0
	v_mov_b32_e32 v116, v0
	v_mov_b32_e32 v117, v0
	v_mov_b32_e32 v118, v0
	v_mov_b32_e32 v119, v0
	v_mov_b32_e32 v120, v0
	v_mov_b32_e32 v121, v0
	v_mov_b32_e32 v130, v0
	v_mov_b32_e32 v131, v0
	v_mov_b32_e32 v132, v0
	v_mov_b32_e32 v133, v0
	v_mov_b32_e32 v134, v0
	v_mov_b32_e32 v135, v0
	v_mov_b32_e32 v136, v0
	v_mov_b32_e32 v137, v0
	v_mov_b32_e32 v88, v0
	v_mov_b32_e32 v89, v0
	v_mov_b32_e32 v90, v0
	v_mov_b32_e32 v91, v0
	v_mov_b32_e32 v92, v0
	v_mov_b32_e32 v93, v0
	v_mov_b32_e32 v94, v0
	v_mov_b32_e32 v95, v0
	v_mov_b32_e32 v106, v0
	v_mov_b32_e32 v107, v0
	v_mov_b32_e32 v108, v0
	v_mov_b32_e32 v109, v0
	v_mov_b32_e32 v110, v0
	v_mov_b32_e32 v111, v0
	v_mov_b32_e32 v112, v0
	v_mov_b32_e32 v113, v0
	v_mov_b32_e32 v122, v0
	v_mov_b32_e32 v123, v0
	v_mov_b32_e32 v124, v0
	v_mov_b32_e32 v125, v0
	v_mov_b32_e32 v126, v0
	v_mov_b32_e32 v127, v0
	v_mov_b32_e32 v128, v0
	v_mov_b32_e32 v129, v0
	v_mov_b32_e32 v138, v0
	v_mov_b32_e32 v139, v0
	v_mov_b32_e32 v140, v0
	v_mov_b32_e32 v141, v0
	v_mov_b32_e32 v142, v0
	v_mov_b32_e32 v143, v0
	v_mov_b32_e32 v144, v0
	v_mov_b32_e32 v145, v0
	v_add_u32_e32 v224, 0x10000, v167
	v_add_u32_e32 v225, 0x14000, v167
	v_add_u32_e32 v226, 0x18000, v167
	v_add_u32_e32 v227, 0x1c000, v167
.LBB0_309:
	s_add_u32 s26, s48, 0xfffc0080
	s_addc_u32 s27, s49, -1
	s_add_i32 s68, 0, 0x10000
	s_cmp_eq_u32 s67, 12
	s_cselect_b32 s53, s19, s27
	s_cselect_b32 s52, s63, s26
	s_cselect_b32 s51, s17, s66
	s_cselect_b32 s50, s64, s65
	s_add_i32 s69, 0, 0x14000
	ds_read_b128 v[56:59], v224
	ds_read_b128 v[60:63], v224 offset:1024
	ds_read_b128 v[68:71], v224 offset:2048
	ds_read_b128 v[72:75], v224 offset:3072
	ds_read_b128 v[158:161], v225
	ds_read_b128 v[162:165], v225 offset:1024
	ds_read_b128 v[170:173], v225 offset:2048
	ds_read_b128 v[174:177], v225 offset:3072
	s_add_i32 m0, s35, 0xc000
	ds_read_b128 v[178:181], v169
	ds_read_b128 v[182:185], v169 offset:1024
	ds_read_b128 v[186:189], v169 offset:2048
	ds_read_b128 v[190:193], v169 offset:3072
	ds_read_b128 v[198:201], v169 offset:4096
	ds_read_b128 v[202:205], v169 offset:5120
	ds_read_b128 v[206:209], v169 offset:6144
	ds_read_b128 v[210:213], v169 offset:7168
	global_load_lds_dwordx4 v154, s[48:49]
	s_add_i32 m0, s35, 0xe000
	s_nop 0
	global_load_lds_dwordx4 v156, s[48:49]
	s_waitcnt vmcnt(8)
	s_waitcnt lgkmcnt(0)
	s_barrier
	s_setprio 1
	s_waitcnt lgkmcnt(0)
	v_mfma_i32_16x16x64_i8 v[142:145], v[56:59], v[178:181], v[142:145]
	v_mfma_i32_16x16x64_i8 v[138:141], v[68:71], v[178:181], v[138:141]
	v_mfma_i32_16x16x64_i8 v[126:129], v[56:59], v[186:189], v[126:129]
	v_mfma_i32_16x16x64_i8 v[122:125], v[68:71], v[186:189], v[122:125]
	v_mfma_i32_16x16x64_i8 v[110:113], v[56:59], v[198:201], v[110:113]
	v_mfma_i32_16x16x64_i8 v[106:109], v[68:71], v[198:201], v[106:109]
	v_mfma_i32_16x16x64_i8 v[92:95], v[56:59], v[206:209], v[92:95]
	v_mfma_i32_16x16x64_i8 v[88:91], v[68:71], v[206:209], v[88:91]
	v_mfma_i32_16x16x64_i8 v[142:145], v[60:63], v[182:185], v[142:145]
	v_mfma_i32_16x16x64_i8 v[138:141], v[72:75], v[182:185], v[138:141]
	v_mfma_i32_16x16x64_i8 v[126:129], v[60:63], v[190:193], v[126:129]
	v_mfma_i32_16x16x64_i8 v[122:125], v[72:75], v[190:193], v[122:125]
	v_mfma_i32_16x16x64_i8 v[110:113], v[60:63], v[202:205], v[110:113]
	v_mfma_i32_16x16x64_i8 v[106:109], v[72:75], v[202:205], v[106:109]
	v_mfma_i32_16x16x64_i8 v[92:95], v[60:63], v[210:213], v[92:95]
	v_mfma_i32_16x16x64_i8 v[88:91], v[72:75], v[210:213], v[88:91]
	s_setprio 0
	s_setprio 1
	v_mfma_i32_16x16x64_i8 v[134:137], v[158:161], v[178:181], v[134:137]
	v_mfma_i32_16x16x64_i8 v[130:133], v[170:173], v[178:181], v[130:133]
	v_mfma_i32_16x16x64_i8 v[118:121], v[158:161], v[186:189], v[118:121]
	v_mfma_i32_16x16x64_i8 v[114:117], v[170:173], v[186:189], v[114:117]
	v_mfma_i32_16x16x64_i8 v[102:105], v[158:161], v[198:201], v[102:105]
	v_mfma_i32_16x16x64_i8 v[98:101], v[170:173], v[198:201], v[98:101]
	v_mfma_i32_16x16x64_i8 v[84:87], v[158:161], v[206:209], v[84:87]
	v_mfma_i32_16x16x64_i8 v[80:83], v[170:173], v[206:209], v[80:83]
	v_mfma_i32_16x16x64_i8 v[134:137], v[162:165], v[182:185], v[134:137]
	v_mfma_i32_16x16x64_i8 v[130:133], v[174:177], v[182:185], v[130:133]
	v_mfma_i32_16x16x64_i8 v[118:121], v[162:165], v[190:193], v[118:121]
	v_mfma_i32_16x16x64_i8 v[114:117], v[174:177], v[190:193], v[114:117]
	v_mfma_i32_16x16x64_i8 v[102:105], v[162:165], v[202:205], v[102:105]
	v_mfma_i32_16x16x64_i8 v[98:101], v[174:177], v[202:205], v[98:101]
	v_mfma_i32_16x16x64_i8 v[84:87], v[162:165], v[210:213], v[84:87]
	v_mfma_i32_16x16x64_i8 v[80:83], v[174:177], v[210:213], v[80:83]
	s_setprio 0
	s_barrier
	s_add_i32 s26, s68, s56
	s_mov_b32 m0, s26
	ds_read_b128 v[178:181], v169 offset:16384
	ds_read_b128 v[182:185], v169 offset:17408
	ds_read_b128 v[186:189], v169 offset:18432
	ds_read_b128 v[190:193], v169 offset:19456
	ds_read_b128 v[198:201], v169 offset:20480
	ds_read_b128 v[202:205], v169 offset:21504
	ds_read_b128 v[206:209], v169 offset:22528
	ds_read_b128 v[210:213], v169 offset:23552
	global_load_lds_dwordx4 v150, s[50:51]
	s_add_i32 m0, s26, 0x2000
	s_add_u32 s26, s50, 0x40000
	s_addc_u32 s27, s51, 0
	s_add_i32 s68, s69, s56
	global_load_lds_dwordx4 v146, s[50:51]
	s_mov_b32 m0, s68
	s_nop 0
	global_load_lds_dwordx4 v150, s[26:27]
	s_add_i32 m0, s68, 0x2000
	s_nop 0
	global_load_lds_dwordx4 v146, s[26:27]
	s_mov_b32 m0, s35
	s_nop 0
	global_load_lds_dwordx4 v152, s[52:53]
	s_mov_b32 m0, s57
	s_nop 0
	global_load_lds_dwordx4 v148, s[52:53]
	s_waitcnt vmcnt(8)
	s_waitcnt lgkmcnt(0)
	s_barrier
	s_setprio 1
	s_waitcnt lgkmcnt(0)
	v_mfma_i32_16x16x64_i8 v[76:79], v[56:59], v[178:181], v[76:79]
	v_mfma_i32_16x16x64_i8 v[64:67], v[68:71], v[178:181], v[64:67]
	v_mfma_i32_16x16x64_i8 v[44:47], v[56:59], v[186:189], v[44:47]
	v_mfma_i32_16x16x64_i8 v[40:43], v[68:71], v[186:189], v[40:43]
	v_mfma_i32_16x16x64_i8 v[28:31], v[56:59], v[198:201], v[28:31]
	v_mfma_i32_16x16x64_i8 v[24:27], v[68:71], v[198:201], v[24:27]
	v_mfma_i32_16x16x64_i8 v[12:15], v[56:59], v[206:209], v[12:15]
	v_mfma_i32_16x16x64_i8 v[8:11], v[68:71], v[206:209], v[8:11]
	v_mfma_i32_16x16x64_i8 v[76:79], v[60:63], v[182:185], v[76:79]
	v_mfma_i32_16x16x64_i8 v[64:67], v[72:75], v[182:185], v[64:67]
	v_mfma_i32_16x16x64_i8 v[44:47], v[60:63], v[190:193], v[44:47]
	v_mfma_i32_16x16x64_i8 v[40:43], v[72:75], v[190:193], v[40:43]
	v_mfma_i32_16x16x64_i8 v[28:31], v[60:63], v[202:205], v[28:31]
	v_mfma_i32_16x16x64_i8 v[24:27], v[72:75], v[202:205], v[24:27]
	v_mfma_i32_16x16x64_i8 v[12:15], v[60:63], v[210:213], v[12:15]
	v_mfma_i32_16x16x64_i8 v[8:11], v[72:75], v[210:213], v[8:11]
	s_setprio 0
	s_setprio 1
	v_mfma_i32_16x16x64_i8 v[52:55], v[158:161], v[178:181], v[52:55]
	v_mfma_i32_16x16x64_i8 v[48:51], v[170:173], v[178:181], v[48:51]
	v_mfma_i32_16x16x64_i8 v[36:39], v[158:161], v[186:189], v[36:39]
	v_mfma_i32_16x16x64_i8 v[32:35], v[170:173], v[186:189], v[32:35]
	v_mfma_i32_16x16x64_i8 v[20:23], v[158:161], v[198:201], v[20:23]
	v_mfma_i32_16x16x64_i8 v[16:19], v[170:173], v[198:201], v[16:19]
	v_mfma_i32_16x16x64_i8 v[4:7], v[158:161], v[206:209], v[4:7]
	v_mfma_i32_16x16x64_i8 v[0:3], v[170:173], v[206:209], v[0:3]
	v_mfma_i32_16x16x64_i8 v[52:55], v[162:165], v[182:185], v[52:55]
	v_mfma_i32_16x16x64_i8 v[48:51], v[174:177], v[182:185], v[48:51]
	v_mfma_i32_16x16x64_i8 v[36:39], v[162:165], v[190:193], v[36:39]
	v_mfma_i32_16x16x64_i8 v[32:35], v[174:177], v[190:193], v[32:35]
	v_mfma_i32_16x16x64_i8 v[20:23], v[162:165], v[202:205], v[20:23]
	v_mfma_i32_16x16x64_i8 v[16:19], v[174:177], v[202:205], v[16:19]
	v_mfma_i32_16x16x64_i8 v[4:7], v[162:165], v[210:213], v[4:7]
	v_mfma_i32_16x16x64_i8 v[0:3], v[174:177], v[210:213], v[0:3]
	s_setprio 0
	s_barrier
	s_add_i32 s68, 0, 0x18000
	s_add_i32 s69, 0, 0x1c000
	ds_read_b128 v[56:59], v226
	ds_read_b128 v[60:63], v226 offset:1024
	ds_read_b128 v[68:71], v226 offset:2048
	ds_read_b128 v[72:75], v226 offset:3072
	ds_read_b128 v[158:161], v227
	ds_read_b128 v[162:165], v227 offset:1024
	ds_read_b128 v[170:173], v227 offset:2048
	ds_read_b128 v[174:177], v227 offset:3072
	s_add_u32 s26, s52, 0x40000
	s_addc_u32 s27, s53, 0
	s_mov_b32 m0, s58
	ds_read_b128 v[178:181], v169 offset:32768
	ds_read_b128 v[182:185], v169 offset:33792
	ds_read_b128 v[186:189], v169 offset:34816
	ds_read_b128 v[190:193], v169 offset:35840
	ds_read_b128 v[198:201], v169 offset:36864
	ds_read_b128 v[202:205], v169 offset:37888
	ds_read_b128 v[206:209], v169 offset:38912
	ds_read_b128 v[210:213], v169 offset:39936
	global_load_lds_dwordx4 v152, s[26:27]
	s_mov_b32 m0, s59
	s_nop 0
	global_load_lds_dwordx4 v148, s[26:27]
	s_waitcnt vmcnt(8)
	s_waitcnt lgkmcnt(0)
	s_barrier
	s_setprio 1
	s_waitcnt lgkmcnt(0)
	v_mfma_i32_16x16x64_i8 v[142:145], v[56:59], v[178:181], v[142:145]
	v_mfma_i32_16x16x64_i8 v[138:141], v[68:71], v[178:181], v[138:141]
	v_mfma_i32_16x16x64_i8 v[126:129], v[56:59], v[186:189], v[126:129]
	v_mfma_i32_16x16x64_i8 v[122:125], v[68:71], v[186:189], v[122:125]
	v_mfma_i32_16x16x64_i8 v[110:113], v[56:59], v[198:201], v[110:113]
	v_mfma_i32_16x16x64_i8 v[106:109], v[68:71], v[198:201], v[106:109]
	v_mfma_i32_16x16x64_i8 v[92:95], v[56:59], v[206:209], v[92:95]
	v_mfma_i32_16x16x64_i8 v[88:91], v[68:71], v[206:209], v[88:91]
	v_mfma_i32_16x16x64_i8 v[142:145], v[60:63], v[182:185], v[142:145]
	v_mfma_i32_16x16x64_i8 v[138:141], v[72:75], v[182:185], v[138:141]
	v_mfma_i32_16x16x64_i8 v[126:129], v[60:63], v[190:193], v[126:129]
	v_mfma_i32_16x16x64_i8 v[122:125], v[72:75], v[190:193], v[122:125]
	v_mfma_i32_16x16x64_i8 v[110:113], v[60:63], v[202:205], v[110:113]
	v_mfma_i32_16x16x64_i8 v[106:109], v[72:75], v[202:205], v[106:109]
	v_mfma_i32_16x16x64_i8 v[92:95], v[60:63], v[210:213], v[92:95]
	v_mfma_i32_16x16x64_i8 v[88:91], v[72:75], v[210:213], v[88:91]
	s_setprio 0
	s_setprio 1
	v_mfma_i32_16x16x64_i8 v[134:137], v[158:161], v[178:181], v[134:137]
	v_mfma_i32_16x16x64_i8 v[130:133], v[170:173], v[178:181], v[130:133]
	v_mfma_i32_16x16x64_i8 v[118:121], v[158:161], v[186:189], v[118:121]
	v_mfma_i32_16x16x64_i8 v[114:117], v[170:173], v[186:189], v[114:117]
	v_mfma_i32_16x16x64_i8 v[102:105], v[158:161], v[198:201], v[102:105]
	v_mfma_i32_16x16x64_i8 v[98:101], v[170:173], v[198:201], v[98:101]
	v_mfma_i32_16x16x64_i8 v[84:87], v[158:161], v[206:209], v[84:87]
	v_mfma_i32_16x16x64_i8 v[80:83], v[170:173], v[206:209], v[80:83]
	v_mfma_i32_16x16x64_i8 v[134:137], v[162:165], v[182:185], v[134:137]
	v_mfma_i32_16x16x64_i8 v[130:133], v[174:177], v[182:185], v[130:133]
	v_mfma_i32_16x16x64_i8 v[118:121], v[162:165], v[190:193], v[118:121]
	v_mfma_i32_16x16x64_i8 v[114:117], v[174:177], v[190:193], v[114:117]
	v_mfma_i32_16x16x64_i8 v[102:105], v[162:165], v[202:205], v[102:105]
	v_mfma_i32_16x16x64_i8 v[98:101], v[174:177], v[202:205], v[98:101]
	v_mfma_i32_16x16x64_i8 v[84:87], v[162:165], v[210:213], v[84:87]
	v_mfma_i32_16x16x64_i8 v[80:83], v[174:177], v[210:213], v[80:83]
	s_setprio 0
	s_barrier
	s_add_i32 s26, s68, s56
	s_add_i32 m0, s26, 0xffffff80
	ds_read_b128 v[178:181], v169 offset:49152
	ds_read_b128 v[182:185], v169 offset:50176
	ds_read_b128 v[186:189], v169 offset:51200
	ds_read_b128 v[190:193], v169 offset:52224
	ds_read_b128 v[198:201], v169 offset:53248
	ds_read_b128 v[202:205], v169 offset:54272
	ds_read_b128 v[206:209], v169 offset:55296
	ds_read_b128 v[210:213], v169 offset:56320
	global_load_lds_dwordx4 v150, s[50:51] offset:128
	s_add_i32 m0, s26, 0x1f80
	s_add_u32 s26, s50, 0x40080
	s_addc_u32 s27, s51, 0
	s_add_i32 s100, s69, s56
	global_load_lds_dwordx4 v146, s[50:51] offset:128
	s_mov_b32 m0, s100
	s_nop 0
	global_load_lds_dwordx4 v150, s[26:27]
	s_add_i32 m0, s100, 0x2000
	s_nop 0
	global_load_lds_dwordx4 v146, s[26:27]
	s_add_i32 m0, s4, 0xffffff80
	s_nop 0
	global_load_lds_dwordx4 v152, s[52:53] offset:128
	s_add_i32 m0, s60, 0xffffff80
	s_nop 0
	global_load_lds_dwordx4 v148, s[52:53] offset:128
	s_waitcnt vmcnt(8)
	s_waitcnt lgkmcnt(0)
	s_barrier
	s_setprio 1
	s_waitcnt lgkmcnt(0)
	v_mfma_i32_16x16x64_i8 v[76:79], v[56:59], v[178:181], v[76:79]
	v_mfma_i32_16x16x64_i8 v[64:67], v[68:71], v[178:181], v[64:67]
	v_mfma_i32_16x16x64_i8 v[44:47], v[56:59], v[186:189], v[44:47]
	v_mfma_i32_16x16x64_i8 v[40:43], v[68:71], v[186:189], v[40:43]
	v_mfma_i32_16x16x64_i8 v[28:31], v[56:59], v[198:201], v[28:31]
	v_mfma_i32_16x16x64_i8 v[24:27], v[68:71], v[198:201], v[24:27]
	v_mfma_i32_16x16x64_i8 v[12:15], v[56:59], v[206:209], v[12:15]
	v_mfma_i32_16x16x64_i8 v[8:11], v[68:71], v[206:209], v[8:11]
	v_mfma_i32_16x16x64_i8 v[76:79], v[60:63], v[182:185], v[76:79]
	v_mfma_i32_16x16x64_i8 v[64:67], v[72:75], v[182:185], v[64:67]
	v_mfma_i32_16x16x64_i8 v[44:47], v[60:63], v[190:193], v[44:47]
	v_mfma_i32_16x16x64_i8 v[40:43], v[72:75], v[190:193], v[40:43]
	v_mfma_i32_16x16x64_i8 v[28:31], v[60:63], v[202:205], v[28:31]
	v_mfma_i32_16x16x64_i8 v[24:27], v[72:75], v[202:205], v[24:27]
	v_mfma_i32_16x16x64_i8 v[12:15], v[60:63], v[210:213], v[12:15]
	v_mfma_i32_16x16x64_i8 v[8:11], v[72:75], v[210:213], v[8:11]
	s_setprio 0
	s_setprio 1
	v_mfma_i32_16x16x64_i8 v[52:55], v[158:161], v[178:181], v[52:55]
	v_mfma_i32_16x16x64_i8 v[48:51], v[170:173], v[178:181], v[48:51]
	v_mfma_i32_16x16x64_i8 v[36:39], v[158:161], v[186:189], v[36:39]
	v_mfma_i32_16x16x64_i8 v[32:35], v[170:173], v[186:189], v[32:35]
	v_mfma_i32_16x16x64_i8 v[20:23], v[158:161], v[198:201], v[20:23]
	v_mfma_i32_16x16x64_i8 v[16:19], v[170:173], v[198:201], v[16:19]
	v_mfma_i32_16x16x64_i8 v[4:7], v[158:161], v[206:209], v[4:7]
	v_mfma_i32_16x16x64_i8 v[0:3], v[170:173], v[206:209], v[0:3]
	v_mfma_i32_16x16x64_i8 v[52:55], v[162:165], v[182:185], v[52:55]
	v_mfma_i32_16x16x64_i8 v[48:51], v[174:177], v[182:185], v[48:51]
	v_mfma_i32_16x16x64_i8 v[36:39], v[162:165], v[190:193], v[36:39]
	v_mfma_i32_16x16x64_i8 v[32:35], v[174:177], v[190:193], v[32:35]
	v_mfma_i32_16x16x64_i8 v[20:23], v[162:165], v[202:205], v[20:23]
	v_mfma_i32_16x16x64_i8 v[16:19], v[174:177], v[202:205], v[16:19]
	v_mfma_i32_16x16x64_i8 v[4:7], v[162:165], v[210:213], v[4:7]
	v_mfma_i32_16x16x64_i8 v[0:3], v[174:177], v[210:213], v[0:3]
	s_setprio 0
	s_barrier
	s_add_i32 s67, s67, 2
	s_add_u32 s48, s48, 0x100
	s_addc_u32 s49, s49, 0
	s_add_u32 s65, s65, 0x100
	s_addc_u32 s66, s66, 0
	s_cmp_gt_u32 s67, 13
	s_cbranch_scc0 .LBB0_309
	s_and_b64 vcc, exec, s[14:15]
	s_cbranch_vccz .LBB0_312
	s_barrier
